# selected-branch softmax: packed (score + (-max)) adds with the negated max in a register (no source modifiers)
# baseline (speedup 1.0000x reference)
.LBB0_630:
	v_mov_b32_e32 v132, v219
	s_nop 1
	v_permlane16_swap_b32_e32 v219, v132
	v_max_f32_e32 v132, v132, v132
	v_max_f32_e32 v133, v219, v219
	v_max_f32_e32 v132, v133, v132
	v_mov_b32_e32 v133, v132
	s_nop 1
	v_permlane32_swap_b32_e32 v132, v133
	v_max3_f32 v219, v218, v132, v133
	v_cndmask_b32_e64 v132, 0, 1, s[20:21]
	v_cmp_ne_u32_e64 s[10:11], 1, v132
	v_xor_b32_e32 v132, 0x80000000, v219
	v_pk_add_f32 v[134:135], v[30:31], v[132:133] op_sel_hi:[1,0]
	v_pk_add_f32 v[142:143], v[174:175], v[132:133] op_sel_hi:[1,0]
	v_pk_add_f32 v[140:141], v[176:177], v[132:133] op_sel_hi:[1,0]
	v_pk_add_f32 v[138:139], v[180:181], v[132:133] op_sel_hi:[1,0]
	v_pk_add_f32 v[136:137], v[182:183], v[132:133] op_sel_hi:[1,0]
	v_pk_add_f32 v[222:223], v[184:185], v[132:133] op_sel_hi:[1,0]
	v_pk_add_f32 v[224:225], v[186:187], v[132:133] op_sel_hi:[1,0]
	v_sub_f32_e32 v226, v178, v219
	s_mov_b64 s[2:3], -1
	s_andn2_b64 vcc, exec, s[20:21]
	v_mul_f32_e32 v146, 0x3fb8aa3b, v134
	v_mul_f32_e32 v145, 0x3fb8aa3b, v135
	v_mul_f32_e32 v144, 0x3fb8aa3b, v142
	v_mul_f32_e32 v143, 0x3fb8aa3b, v143
	v_mul_f32_e32 v142, 0x3fb8aa3b, v140
	v_mul_f32_e32 v141, 0x3fb8aa3b, v141
	v_mul_f32_e32 v140, 0x3fb8aa3b, v138
	v_mul_f32_e32 v139, 0x3fb8aa3b, v139
	v_mul_f32_e32 v138, 0x3fb8aa3b, v136
	v_mul_f32_e32 v137, 0x3fb8aa3b, v137
	v_mul_f32_e32 v136, 0x3fb8aa3b, v222
	v_mul_f32_e32 v135, 0x3fb8aa3b, v223
	v_mul_f32_e32 v134, 0x3fb8aa3b, v224
	v_mul_f32_e32 v133, 0x3fb8aa3b, v225
	v_mul_f32_e32 v132, 0x3fb8aa3b, v226
	s_cbranch_vccnz .LBB0_632
	v_cmp_lt_f32_e32 vcc, s51, v30
	v_exp_f32_e32 v30, v146
	v_cmp_lt_f32_e64 s[0:1], s51, v179
	s_mov_b64 s[2:3], 0
	v_cndmask_b32_e32 v221, 0, v30, vcc
	v_cmp_lt_f32_e32 vcc, s51, v31
	v_exp_f32_e32 v31, v145
	v_add_f32_e32 v30, 0, v221
	v_cndmask_b32_e32 v222, 0, v31, vcc
	v_exp_f32_e32 v31, v144
	v_cmp_lt_f32_e32 vcc, s51, v174
	v_add_f32_e32 v30, v222, v30
	s_nop 0
	v_cndmask_b32_e32 v223, 0, v31, vcc
	v_exp_f32_e32 v31, v143
	v_cmp_lt_f32_e32 vcc, s51, v175
	v_add_f32_e32 v30, v223, v30
	s_nop 0
	v_cndmask_b32_e32 v224, 0, v31, vcc
	v_exp_f32_e32 v31, v142
	v_cmp_lt_f32_e32 vcc, s51, v176
	v_add_f32_e32 v30, v224, v30
	s_nop 0
	v_cndmask_b32_e32 v225, 0, v31, vcc
	v_exp_f32_e32 v31, v141
	v_cmp_lt_f32_e32 vcc, s51, v177
	v_add_f32_e32 v30, v225, v30
	s_nop 0
	v_cndmask_b32_e32 v227, 0, v31, vcc
	v_exp_f32_e32 v31, v140
	v_cmp_lt_f32_e32 vcc, s51, v180
	v_add_f32_e32 v30, v227, v30
	s_nop 0
	v_cndmask_b32_e32 v229, 0, v31, vcc
	v_exp_f32_e32 v31, v139
	v_cmp_lt_f32_e32 vcc, s51, v181
	v_add_f32_e32 v30, v229, v30
	s_nop 0
	v_cndmask_b32_e32 v231, 0, v31, vcc
	v_exp_f32_e32 v31, v138
	v_cmp_lt_f32_e32 vcc, s51, v182
	v_add_f32_e32 v30, v231, v30
	s_nop 0
	v_cndmask_b32_e32 v226, 0, v31, vcc
	v_exp_f32_e32 v31, v137
	v_cmp_lt_f32_e32 vcc, s51, v183
	v_add_f32_e32 v30, v226, v30
	s_nop 0
	v_cndmask_b32_e32 v228, 0, v31, vcc
	v_exp_f32_e32 v31, v136
	v_cmp_lt_f32_e32 vcc, s51, v184
	v_add_f32_e32 v30, v228, v30
	s_nop 0
	v_cndmask_b32_e32 v230, 0, v31, vcc
	v_exp_f32_e32 v31, v135
	v_cmp_lt_f32_e32 vcc, s51, v185
	v_add_f32_e32 v30, v230, v30
	s_nop 0
	v_cndmask_b32_e32 v232, 0, v31, vcc
	v_exp_f32_e32 v31, v134
	v_cmp_lt_f32_e32 vcc, s51, v186
	v_add_f32_e32 v30, v232, v30
	s_nop 0
	v_cndmask_b32_e32 v233, 0, v31, vcc
	v_exp_f32_e32 v31, v133
	v_cmp_lt_f32_e32 vcc, s51, v187
	v_add_f32_e32 v30, v233, v30
	s_nop 0
	v_cndmask_b32_e32 v234, 0, v31, vcc
	v_exp_f32_e32 v31, v132
	v_cmp_lt_f32_e32 vcc, s51, v178
	v_add_f32_e32 v30, v234, v30
	s_nop 0
	v_cndmask_b32_e32 v235, 0, v31, vcc
	v_add_f32_e32 v147, v235, v30

.LBB0_640:
	v_mov_b32_e32 v116, v176
	s_nop 1
	v_permlane16_swap_b32_e32 v176, v116
	v_max_f32_e32 v116, v116, v116
	v_max_f32_e32 v117, v176, v176
	v_max_f32_e32 v116, v117, v116
	v_mov_b32_e32 v117, v116
	s_nop 1
	v_permlane32_swap_b32_e32 v116, v117
	v_max3_f32 v220, v217, v116, v117
	v_xor_b32_e32 v116, 0x80000000, v220
	v_pk_add_f32 v[118:119], v[132:133], v[116:117] op_sel_hi:[1,0]
	v_pk_add_f32 v[120:121], v[134:135], v[116:117] op_sel_hi:[1,0]
	v_pk_add_f32 v[122:123], v[136:137], v[116:117] op_sel_hi:[1,0]
	v_pk_add_f32 v[124:125], v[140:141], v[116:117] op_sel_hi:[1,0]
	v_pk_add_f32 v[130:131], v[142:143], v[116:117] op_sel_hi:[1,0]
	v_pk_add_f32 v[128:129], v[144:145], v[116:117] op_sel_hi:[1,0]
	v_pk_add_f32 v[126:127], v[146:147], v[116:117] op_sel_hi:[1,0]
	v_sub_f32_e32 v187, v138, v220
	s_mov_b64 s[2:3], -1
	s_and_b64 vcc, exec, s[10:11]
	v_mul_f32_e32 v186, 0x3fb8aa3b, v118
	v_mul_f32_e32 v185, 0x3fb8aa3b, v119
	v_mul_f32_e32 v184, 0x3fb8aa3b, v120
	v_mul_f32_e32 v183, 0x3fb8aa3b, v121
	v_mul_f32_e32 v182, 0x3fb8aa3b, v122
	v_mul_f32_e32 v181, 0x3fb8aa3b, v123
	v_mul_f32_e32 v180, 0x3fb8aa3b, v124
	v_mul_f32_e32 v179, 0x3fb8aa3b, v125
	v_mul_f32_e32 v178, 0x3fb8aa3b, v130
	v_mul_f32_e32 v177, 0x3fb8aa3b, v131
	v_mul_f32_e32 v131, 0x3fb8aa3b, v128
	v_mul_f32_e32 v130, 0x3fb8aa3b, v129
	v_mul_f32_e32 v129, 0x3fb8aa3b, v126
	v_mul_f32_e32 v117, 0x3fb8aa3b, v127
	v_mul_f32_e32 v116, 0x3fb8aa3b, v187
	s_cbranch_vccnz .LBB0_642
	v_exp_f32_e32 v118, v186
	v_exp_f32_e32 v119, v185
	v_cmp_lt_f32_e32 vcc, s51, v132
	v_exp_f32_e32 v124, v181
	v_exp_f32_e32 v125, v180
	v_cndmask_b32_e32 v118, 0, v118, vcc
	v_cmp_lt_f32_e32 vcc, s51, v133
	v_add_f32_e32 v120, 0, v118
	v_exp_f32_e32 v133, v130
	v_cndmask_b32_e32 v119, 0, v119, vcc
	v_add_f32_e32 v121, v119, v120
	v_exp_f32_e32 v120, v184
	v_cmp_lt_f32_e32 vcc, s51, v134
	v_cmp_lt_f32_e64 s[0:1], s51, v139
	s_mov_b64 s[2:3], 0
	v_cndmask_b32_e32 v120, 0, v120, vcc
	v_add_f32_e32 v122, v120, v121
	v_exp_f32_e32 v121, v183
	v_cmp_lt_f32_e32 vcc, s51, v135
	s_nop 1
	v_cndmask_b32_e32 v121, 0, v121, vcc
	v_add_f32_e32 v123, v121, v122
	v_exp_f32_e32 v122, v182
	v_cmp_lt_f32_e32 vcc, s51, v136
	s_nop 1
	v_cndmask_b32_e32 v122, 0, v122, vcc
	v_cmp_lt_f32_e32 vcc, s51, v137
	v_add_f32_e32 v123, v122, v123
	s_nop 0
	v_cndmask_b32_e32 v124, 0, v124, vcc
	v_cmp_lt_f32_e32 vcc, s51, v140
	v_add_f32_e32 v123, v124, v123
	s_nop 0
	v_cndmask_b32_e32 v126, 0, v125, vcc
	v_exp_f32_e32 v125, v179
	v_cmp_lt_f32_e32 vcc, s51, v141
	v_add_f32_e32 v123, v126, v123
	s_nop 0
	v_cndmask_b32_e32 v128, 0, v125, vcc
	v_add_f32_e32 v125, v128, v123
	v_exp_f32_e32 v123, v178
	v_cmp_lt_f32_e32 vcc, s51, v142
	s_nop 1
	v_cndmask_b32_e32 v123, 0, v123, vcc
	v_add_f32_e32 v127, v123, v125
	v_exp_f32_e32 v125, v177
	v_cmp_lt_f32_e32 vcc, s51, v143
	s_nop 1
	v_cndmask_b32_e32 v125, 0, v125, vcc
	v_add_f32_e32 v132, v125, v127
	v_exp_f32_e32 v127, v131
	v_cmp_lt_f32_e32 vcc, s51, v144
	s_nop 1
	v_cndmask_b32_e32 v127, 0, v127, vcc
	v_cmp_lt_f32_e32 vcc, s51, v145
	v_add_f32_e32 v132, v127, v132
	s_nop 0
	v_cndmask_b32_e32 v176, 0, v133, vcc
	v_exp_f32_e32 v133, v129
	v_cmp_lt_f32_e32 vcc, s51, v146
	v_add_f32_e32 v132, v176, v132
	s_nop 0
	v_cndmask_b32_e32 v187, 0, v133, vcc
	v_exp_f32_e32 v133, v117
	v_cmp_lt_f32_e32 vcc, s51, v147
	v_add_f32_e32 v132, v187, v132
	s_nop 0
	v_cndmask_b32_e32 v218, 0, v133, vcc
	v_exp_f32_e32 v133, v116
	v_cmp_lt_f32_e32 vcc, s51, v138
	v_add_f32_e32 v132, v218, v132
	s_nop 0
	v_cndmask_b32_e32 v236, 0, v133, vcc
	v_add_f32_e32 v237, v236, v132

.LBB0_658:
	v_mov_b32_e32 v132, v218
	s_nop 1
	v_permlane16_swap_b32_e32 v218, v132
	v_max_f32_e32 v132, v132, v132
	v_max_f32_e32 v133, v218, v218
	v_max_f32_e32 v132, v133, v132
	v_mov_b32_e32 v133, v132
	s_nop 1
	v_permlane32_swap_b32_e32 v132, v133
	v_max3_f32 v218, v219, v132, v133
	v_cndmask_b32_e64 v132, 0, 1, s[18:19]
	v_cmp_ne_u32_e64 s[10:11], 1, v132
	v_xor_b32_e32 v132, 0x80000000, v218
	v_pk_add_f32 v[134:135], v[30:31], v[132:133] op_sel_hi:[1,0]
	v_pk_add_f32 v[142:143], v[174:175], v[132:133] op_sel_hi:[1,0]
	v_pk_add_f32 v[140:141], v[176:177], v[132:133] op_sel_hi:[1,0]
	v_pk_add_f32 v[138:139], v[180:181], v[132:133] op_sel_hi:[1,0]
	v_pk_add_f32 v[136:137], v[182:183], v[132:133] op_sel_hi:[1,0]
	v_pk_add_f32 v[222:223], v[184:185], v[132:133] op_sel_hi:[1,0]
	v_pk_add_f32 v[224:225], v[186:187], v[132:133] op_sel_hi:[1,0]
	v_sub_f32_e32 v226, v178, v218
	s_mov_b64 s[2:3], -1
	s_andn2_b64 vcc, exec, s[18:19]
	v_mul_f32_e32 v146, 0x3fb8aa3b, v134
	v_mul_f32_e32 v145, 0x3fb8aa3b, v135
	v_mul_f32_e32 v144, 0x3fb8aa3b, v142
	v_mul_f32_e32 v143, 0x3fb8aa3b, v143
	v_mul_f32_e32 v142, 0x3fb8aa3b, v140
	v_mul_f32_e32 v141, 0x3fb8aa3b, v141
	v_mul_f32_e32 v140, 0x3fb8aa3b, v138
	v_mul_f32_e32 v139, 0x3fb8aa3b, v139
	v_mul_f32_e32 v138, 0x3fb8aa3b, v136
	v_mul_f32_e32 v137, 0x3fb8aa3b, v137
	v_mul_f32_e32 v136, 0x3fb8aa3b, v222
	v_mul_f32_e32 v135, 0x3fb8aa3b, v223
	v_mul_f32_e32 v134, 0x3fb8aa3b, v224
	v_mul_f32_e32 v133, 0x3fb8aa3b, v225
	v_mul_f32_e32 v132, 0x3fb8aa3b, v226
	s_cbranch_vccnz .LBB0_660
	v_cmp_lt_f32_e32 vcc, s51, v30
	v_exp_f32_e32 v30, v146
	v_cmp_lt_f32_e64 s[0:1], s51, v179
	s_mov_b64 s[2:3], 0
	v_cndmask_b32_e32 v221, 0, v30, vcc
	v_cmp_lt_f32_e32 vcc, s51, v31
	v_exp_f32_e32 v31, v145
	v_add_f32_e32 v30, 0, v221
	v_cndmask_b32_e32 v222, 0, v31, vcc
	v_exp_f32_e32 v31, v144
	v_cmp_lt_f32_e32 vcc, s51, v174
	v_add_f32_e32 v30, v222, v30
	s_nop 0
	v_cndmask_b32_e32 v223, 0, v31, vcc
	v_exp_f32_e32 v31, v143
	v_cmp_lt_f32_e32 vcc, s51, v175
	v_add_f32_e32 v30, v223, v30
	s_nop 0
	v_cndmask_b32_e32 v224, 0, v31, vcc
	v_exp_f32_e32 v31, v142
	v_cmp_lt_f32_e32 vcc, s51, v176
	v_add_f32_e32 v30, v224, v30
	s_nop 0
	v_cndmask_b32_e32 v225, 0, v31, vcc
	v_exp_f32_e32 v31, v141
	v_cmp_lt_f32_e32 vcc, s51, v177
	v_add_f32_e32 v30, v225, v30
	s_nop 0
	v_cndmask_b32_e32 v227, 0, v31, vcc
	v_exp_f32_e32 v31, v140
	v_cmp_lt_f32_e32 vcc, s51, v180
	v_add_f32_e32 v30, v227, v30
	s_nop 0
	v_cndmask_b32_e32 v229, 0, v31, vcc
	v_exp_f32_e32 v31, v139
	v_cmp_lt_f32_e32 vcc, s51, v181
	v_add_f32_e32 v30, v229, v30
	s_nop 0
	v_cndmask_b32_e32 v231, 0, v31, vcc
	v_exp_f32_e32 v31, v138
	v_cmp_lt_f32_e32 vcc, s51, v182
	v_add_f32_e32 v30, v231, v30
	s_nop 0
	v_cndmask_b32_e32 v226, 0, v31, vcc
	v_exp_f32_e32 v31, v137
	v_cmp_lt_f32_e32 vcc, s51, v183
	v_add_f32_e32 v30, v226, v30
	s_nop 0
	v_cndmask_b32_e32 v228, 0, v31, vcc
	v_exp_f32_e32 v31, v136
	v_cmp_lt_f32_e32 vcc, s51, v184
	v_add_f32_e32 v30, v228, v30
	s_nop 0
	v_cndmask_b32_e32 v230, 0, v31, vcc
	v_exp_f32_e32 v31, v135
	v_cmp_lt_f32_e32 vcc, s51, v185
	v_add_f32_e32 v30, v230, v30
	s_nop 0
	v_cndmask_b32_e32 v232, 0, v31, vcc
	v_exp_f32_e32 v31, v134
	v_cmp_lt_f32_e32 vcc, s51, v186
	v_add_f32_e32 v30, v232, v30
	s_nop 0
	v_cndmask_b32_e32 v233, 0, v31, vcc
	v_exp_f32_e32 v31, v133
	v_cmp_lt_f32_e32 vcc, s51, v187
	v_add_f32_e32 v30, v233, v30
	s_nop 0
	v_cndmask_b32_e32 v234, 0, v31, vcc
	v_exp_f32_e32 v31, v132
	v_cmp_lt_f32_e32 vcc, s51, v178
	v_add_f32_e32 v30, v234, v30
	s_nop 0
	v_cndmask_b32_e32 v235, 0, v31, vcc
	v_add_f32_e32 v147, v235, v30

.LBB0_668:
	v_mov_b32_e32 v116, v176
	s_nop 1
	v_permlane16_swap_b32_e32 v176, v116
	v_max_f32_e32 v116, v116, v116
	v_max_f32_e32 v117, v176, v176
	v_max_f32_e32 v116, v117, v116
	v_mov_b32_e32 v117, v116
	s_nop 1
	v_permlane32_swap_b32_e32 v116, v117
	v_max3_f32 v217, v220, v116, v117
	v_xor_b32_e32 v116, 0x80000000, v217
	v_pk_add_f32 v[118:119], v[132:133], v[116:117] op_sel_hi:[1,0]
	v_pk_add_f32 v[120:121], v[134:135], v[116:117] op_sel_hi:[1,0]
	v_pk_add_f32 v[122:123], v[136:137], v[116:117] op_sel_hi:[1,0]
	v_pk_add_f32 v[124:125], v[140:141], v[116:117] op_sel_hi:[1,0]
	v_pk_add_f32 v[128:129], v[142:143], v[116:117] op_sel_hi:[1,0]
	v_pk_add_f32 v[130:131], v[144:145], v[116:117] op_sel_hi:[1,0]
	v_pk_add_f32 v[126:127], v[146:147], v[116:117] op_sel_hi:[1,0]
	v_sub_f32_e32 v187, v138, v217
	s_mov_b64 s[2:3], -1
	s_and_b64 vcc, exec, s[10:11]
	v_mul_f32_e32 v186, 0x3fb8aa3b, v118
	v_mul_f32_e32 v185, 0x3fb8aa3b, v119
	v_mul_f32_e32 v184, 0x3fb8aa3b, v120
	v_mul_f32_e32 v183, 0x3fb8aa3b, v121
	v_mul_f32_e32 v182, 0x3fb8aa3b, v122
	v_mul_f32_e32 v181, 0x3fb8aa3b, v123
	v_mul_f32_e32 v180, 0x3fb8aa3b, v124
	v_mul_f32_e32 v179, 0x3fb8aa3b, v125
	v_mul_f32_e32 v178, 0x3fb8aa3b, v128
	v_mul_f32_e32 v177, 0x3fb8aa3b, v129
	v_mul_f32_e32 v176, 0x3fb8aa3b, v130
	v_mul_f32_e32 v130, 0x3fb8aa3b, v131
	v_mul_f32_e32 v129, 0x3fb8aa3b, v126
	v_mul_f32_e32 v117, 0x3fb8aa3b, v127
	v_mul_f32_e32 v116, 0x3fb8aa3b, v187
	s_cbranch_vccnz .LBB0_670
	v_exp_f32_e32 v118, v186
	v_exp_f32_e32 v119, v185
	v_cmp_lt_f32_e32 vcc, s51, v132
	v_exp_f32_e32 v124, v181
	v_exp_f32_e32 v125, v180
	v_cndmask_b32_e32 v118, 0, v118, vcc
	v_cmp_lt_f32_e32 vcc, s51, v133
	v_add_f32_e32 v120, 0, v118
	v_exp_f32_e32 v133, v129
	v_cndmask_b32_e32 v119, 0, v119, vcc
	v_add_f32_e32 v121, v119, v120
	v_exp_f32_e32 v120, v184
	v_cmp_lt_f32_e32 vcc, s51, v134
	v_cmp_lt_f32_e64 s[0:1], s51, v139
	s_mov_b64 s[2:3], 0
	v_cndmask_b32_e32 v120, 0, v120, vcc
	v_add_f32_e32 v122, v120, v121
	v_exp_f32_e32 v121, v183
	v_cmp_lt_f32_e32 vcc, s51, v135
	s_nop 1
	v_cndmask_b32_e32 v121, 0, v121, vcc
	v_add_f32_e32 v123, v121, v122
	v_exp_f32_e32 v122, v182
	v_cmp_lt_f32_e32 vcc, s51, v136
	s_nop 1
	v_cndmask_b32_e32 v122, 0, v122, vcc
	v_cmp_lt_f32_e32 vcc, s51, v137
	v_add_f32_e32 v123, v122, v123
	s_nop 0
	v_cndmask_b32_e32 v124, 0, v124, vcc
	v_cmp_lt_f32_e32 vcc, s51, v140
	v_add_f32_e32 v123, v124, v123
	s_nop 0
	v_cndmask_b32_e32 v126, 0, v125, vcc
	v_exp_f32_e32 v125, v179
	v_cmp_lt_f32_e32 vcc, s51, v141
	v_add_f32_e32 v123, v126, v123
	s_nop 0
	v_cndmask_b32_e32 v128, 0, v125, vcc
	v_add_f32_e32 v125, v128, v123
	v_exp_f32_e32 v123, v178
	v_cmp_lt_f32_e32 vcc, s51, v142
	s_nop 1
	v_cndmask_b32_e32 v123, 0, v123, vcc
	v_add_f32_e32 v127, v123, v125
	v_exp_f32_e32 v125, v177
	v_cmp_lt_f32_e32 vcc, s51, v143
	s_nop 1
	v_cndmask_b32_e32 v125, 0, v125, vcc
	v_add_f32_e32 v131, v125, v127
	v_exp_f32_e32 v127, v176
	v_cmp_lt_f32_e32 vcc, s51, v144
	s_nop 1
	v_cndmask_b32_e32 v127, 0, v127, vcc
	v_add_f32_e32 v132, v127, v131
	v_exp_f32_e32 v131, v130
	v_cmp_lt_f32_e32 vcc, s51, v145
	s_nop 1
	v_cndmask_b32_e32 v131, 0, v131, vcc
	v_cmp_lt_f32_e32 vcc, s51, v146
	v_add_f32_e32 v132, v131, v132
	s_nop 0
	v_cndmask_b32_e32 v187, 0, v133, vcc
	v_exp_f32_e32 v133, v117
	v_cmp_lt_f32_e32 vcc, s51, v147
	v_add_f32_e32 v132, v187, v132
	s_nop 0
	v_cndmask_b32_e32 v219, 0, v133, vcc
	v_exp_f32_e32 v133, v116
	v_cmp_lt_f32_e32 vcc, s51, v138
	v_add_f32_e32 v132, v219, v132
	s_nop 0
	v_cndmask_b32_e32 v236, 0, v133, vcc
	v_add_f32_e32 v237, v236, v132
